# k36: k35 + attention tile-loop exit no longer waits for the unused in-flight K/V register tiles (epilogue scratch registers moved off the staging registers)
# baseline (speedup 1.0000x reference)
; #define LAS __attribute__((address_space(3)))
; __device__ __forceinline__ int crow(int r, int hi) { return (r & 3) + 8 * (r >> 2) + 4 * hi; }
; __device__ __forceinline__ void attn_unit(const UnitDesc& u, LAS unsigned char* shm, float qkmax, float thresh) {
;     ...
;         LAS float* lx = (LAS float*)(shm + LDS_LX) + wid * 32;
;         if (hi == 0) lx[r32] = l_reg;
;         asm volatile("s_waitcnt lgkmcnt(0)" ::: "memory");
;         float rli[16];
; #pragma unroll
;         for (int r = 0; r < 16; ++r) rli[r] = 1.f / lx[crow(r, hi)];
.LBB0_718:
	s_or_b64 exec, exec, s[8:9]
	s_waitcnt lgkmcnt(0)
	v_lshl_add_u32 v21, v142, 2, s10
	ds_read_b128 v[22:25], v21 offset:36864
	ds_read_b128 v[26:29], v21 offset:36896
	s_lshl_b64 s[8:9], s[34:35], 11
	s_add_u32 s8, s92, s8
	s_addc_u32 s10, s93, s9
	s_add_u32 s6, s8, s6
	s_waitcnt lgkmcnt(1)
	v_div_scale_f32 v30, s[8:9], v22, v22, 1.0
	v_rcp_f32_e32 v31, v30
	s_addc_u32 s7, s10, s7
	s_add_u32 s6, s6, 0x1800400
	s_addc_u32 s7, s7, 0
	v_fma_f32 v32, -v30, v31, 1.0
	v_fmac_f32_e32 v31, v32, v31
	v_div_scale_f32 v32, vcc, 1.0, v22, 1.0
	v_mul_f32_e32 v33, v32, v31
	v_fma_f32 v240, -v30, v33, v32
	v_fmac_f32_e32 v33, v240, v31
	v_fma_f32 v30, -v30, v33, v32
	v_div_scale_f32 v32, s[8:9], v23, v23, 1.0
	v_rcp_f32_e32 v240, v32
	v_div_fmas_f32 v30, v30, v31, v33
	v_div_fixup_f32 v241, v30, v22, 1.0
	v_mul_f32_e32 v34, v34, v241
	v_fma_f32 v22, -v32, v240, 1.0
	v_fmac_f32_e32 v240, v22, v240
	v_div_scale_f32 v22, vcc, 1.0, v23, 1.0
	v_mul_f32_e32 v30, v22, v240
	v_fma_f32 v31, -v32, v30, v22
	v_fmac_f32_e32 v30, v31, v240
	v_div_scale_f32 v31, s[8:9], v24, v24, 1.0
	v_fma_f32 v22, -v32, v30, v22
	v_rcp_f32_e32 v32, v31
	v_div_fmas_f32 v22, v22, v240, v30
	v_div_fixup_f32 v240, v22, v23, 1.0
	v_lshlrev_b64 v[18:19], 11, v[18:19]
	v_fma_f32 v22, -v31, v32, 1.0
	v_fmac_f32_e32 v32, v22, v32
	v_div_scale_f32 v22, vcc, 1.0, v24, 1.0
	v_mul_f32_e32 v23, v22, v32
	v_fma_f32 v30, -v31, v23, v22
	v_fmac_f32_e32 v23, v30, v32
	v_div_scale_f32 v30, s[8:9], v25, v25, 1.0
	v_fma_f32 v22, -v31, v23, v22
	v_rcp_f32_e32 v31, v30
	v_div_fmas_f32 v22, v22, v32, v23
	v_div_fixup_f32 v242, v22, v24, 1.0
	v_lshl_add_u64 v[18:19], s[6:7], 0, v[18:19]
	v_fma_f32 v22, -v30, v31, 1.0
	v_fmac_f32_e32 v31, v22, v31
	v_div_scale_f32 v22, vcc, 1.0, v25, 1.0
	v_mul_f32_e32 v23, v22, v31
	v_fma_f32 v24, -v30, v23, v22
	v_fmac_f32_e32 v23, v24, v31
	s_waitcnt lgkmcnt(0)
	v_div_scale_f32 v24, s[8:9], v26, v26, 1.0
	v_fma_f32 v22, -v30, v23, v22
	v_rcp_f32_e32 v30, v24
	v_div_fmas_f32 v22, v22, v31, v23
	v_div_fixup_f32 v243, v22, v25, 1.0
	v_div_scale_f32 v31, s[8:9], v29, v29, 1.0
	v_fma_f32 v22, -v24, v30, 1.0
	v_fmac_f32_e32 v30, v22, v30
	v_div_scale_f32 v22, vcc, 1.0, v26, 1.0
	v_mul_f32_e32 v23, v22, v30
	v_fma_f32 v25, -v24, v23, v22
	v_fmac_f32_e32 v23, v25, v30
	v_fma_f32 v22, -v24, v23, v22
	v_div_scale_f32 v24, s[8:9], v27, v27, 1.0
	v_rcp_f32_e32 v25, v24
	v_div_fmas_f32 v22, v22, v30, v23
	v_div_fixup_f32 v26, v22, v26, 1.0
	v_rcp_f32_e32 v244, v31
	v_fma_f32 v22, -v24, v25, 1.0
	v_fmac_f32_e32 v25, v22, v25
	v_div_scale_f32 v22, vcc, 1.0, v27, 1.0
	v_mul_f32_e32 v23, v22, v25
	v_fma_f32 v30, -v24, v23, v22
	v_fmac_f32_e32 v23, v30, v25
	v_fma_f32 v22, -v24, v23, v22
	v_div_scale_f32 v24, s[8:9], v28, v28, 1.0
	v_rcp_f32_e32 v30, v24
	v_div_fmas_f32 v22, v22, v25, v23
	v_div_fixup_f32 v27, v22, v27, 1.0
	v_lshl_add_u64 v[18:19], v[18:19], 0, v[0:1]
	v_fma_f32 v22, -v24, v30, 1.0
	v_fmac_f32_e32 v30, v22, v30
	v_div_scale_f32 v22, vcc, 1.0, v28, 1.0
	v_mul_f32_e32 v23, v22, v30
	v_fma_f32 v25, -v24, v23, v22
	v_fmac_f32_e32 v23, v25, v30
	v_fma_f32 v22, -v24, v23, v22
	v_div_fmas_f32 v22, v22, v30, v23
	v_div_fixup_f32 v28, v22, v28, 1.0
	v_fma_f32 v22, -v31, v244, 1.0
	v_fmac_f32_e32 v244, v22, v244
	ds_read_b128 v[22:25], v21 offset:36928
	v_div_scale_f32 v30, vcc, 1.0, v29, 1.0
	v_mul_f32_e32 v245, v30, v244
	v_fma_f32 v32, -v31, v245, v30
	v_fmac_f32_e32 v245, v32, v244
	v_fma_f32 v246, -v31, v245, v30
	ds_read_b128 v[30:33], v21 offset:36960
	s_waitcnt lgkmcnt(1)
	v_div_scale_f32 v21, s[8:9], v22, v22, 1.0
	v_rcp_f32_e32 v247, v21
	v_div_fmas_f32 v244, v246, v244, v245
	v_div_fixup_f32 v29, v244, v29, 1.0
	v_fma_f32 v244, -v21, v247, 1.0
	v_fmac_f32_e32 v247, v244, v247
	v_div_scale_f32 v244, vcc, 1.0, v22, 1.0
	v_mul_f32_e32 v245, v244, v247
	v_fma_f32 v246, -v21, v245, v244
	v_fmac_f32_e32 v245, v246, v247
	v_fma_f32 v21, -v21, v245, v244
	v_div_scale_f32 v244, s[8:9], v23, v23, 1.0
	v_rcp_f32_e32 v246, v244
	v_div_fmas_f32 v21, v21, v247, v245
	v_div_fixup_f32 v21, v21, v22, 1.0
	v_fma_f32 v22, -v244, v246, 1.0
	v_fmac_f32_e32 v246, v22, v246
	v_div_scale_f32 v22, vcc, 1.0, v23, 1.0
	v_mul_f32_e32 v245, v22, v246
	v_fma_f32 v247, -v244, v245, v22
	v_fmac_f32_e32 v245, v247, v246
	v_fma_f32 v22, -v244, v245, v22
	v_div_scale_f32 v244, s[8:9], v24, v24, 1.0
	v_rcp_f32_e32 v247, v244
	v_div_fmas_f32 v22, v22, v246, v245
	v_div_fixup_f32 v22, v22, v23, 1.0
	v_fma_f32 v23, -v244, v247, 1.0
	v_fmac_f32_e32 v247, v23, v247
	v_div_scale_f32 v23, vcc, 1.0, v24, 1.0
	v_mul_f32_e32 v245, v23, v247
	v_fma_f32 v246, -v244, v245, v23
	v_fmac_f32_e32 v245, v246, v247
	v_fma_f32 v23, -v244, v245, v23
	v_div_scale_f32 v244, s[8:9], v25, v25, 1.0
	v_rcp_f32_e32 v246, v244
	v_div_fmas_f32 v23, v23, v247, v245
	v_div_fixup_f32 v23, v23, v24, 1.0
	v_fma_f32 v24, -v244, v246, 1.0
	v_fmac_f32_e32 v246, v24, v246
	v_div_scale_f32 v24, vcc, 1.0, v25, 1.0
	v_mul_f32_e32 v245, v24, v246
	v_fma_f32 v247, -v244, v245, v24
	v_fmac_f32_e32 v245, v247, v246
	v_fma_f32 v24, -v244, v245, v24
	s_waitcnt lgkmcnt(0)
; #define LAS __attribute__((address_space(3)))
; __device__ __forceinline__ unsigned f2bf(float f) { unsigned u = __builtin_bit_cast(unsigned, f); return (u + 0x7fffu + ((u >> 16) & 1u)) >> 16; }
; __device__ __forceinline__ int crow(int r, int hi) { return (r & 3) + 8 * (r >> 2) + 4 * hi; }
; __device__ __forceinline__ void attn_unit(const UnitDesc& u, LAS unsigned char* shm, float qkmax, float thresh) {
;     ...
;         for (int r = 0; r < 16; ++r) rli[r] = 1.f / lx[crow(r, hi)];
;         LAS bf16_t* stg = (LAS bf16_t*)(shm + LDS_OST) + wid * 2048;
; #pragma unroll
;         for (int r = 0; r < 16; ++r) { const int orow = crow(r, hi);
; #pragma unroll
;             for (int d0 = 0; d0 < 2; ++d0) stg[orow * 64 + d0 * 32 + r32] = (bf16_t)f2bf(o[d0][r] * rli[r]); }
	v_div_scale_f32 v244, s[8:9], v30, v30, 1.0
	v_rcp_f32_e32 v247, v244
	v_div_fmas_f32 v24, v24, v246, v245
	v_div_fixup_f32 v24, v24, v25, 1.0
	v_fma_f32 v25, -v244, v247, 1.0
	v_fmac_f32_e32 v247, v25, v247
	v_div_scale_f32 v25, vcc, 1.0, v30, 1.0
	v_mul_f32_e32 v245, v25, v247
	v_fma_f32 v246, -v244, v245, v25
	v_fmac_f32_e32 v245, v246, v247
	v_fma_f32 v25, -v244, v245, v25
	v_div_scale_f32 v244, s[8:9], v31, v31, 1.0
	v_rcp_f32_e32 v246, v244
	v_div_fmas_f32 v25, v25, v247, v245
	v_div_fixup_f32 v25, v25, v30, 1.0
	v_fma_f32 v30, -v244, v246, 1.0
	v_fmac_f32_e32 v246, v30, v246
	v_div_scale_f32 v30, vcc, 1.0, v31, 1.0
	v_mul_f32_e32 v245, v30, v246
	v_fma_f32 v247, -v244, v245, v30
	v_fmac_f32_e32 v245, v247, v246
	v_fma_f32 v30, -v244, v245, v30
	v_div_scale_f32 v244, s[8:9], v32, v32, 1.0
	v_rcp_f32_e32 v247, v244
	v_div_fmas_f32 v30, v30, v246, v245
	v_div_fixup_f32 v30, v30, v31, 1.0
	v_fma_f32 v31, -v244, v247, 1.0
	v_fmac_f32_e32 v247, v31, v247
	v_div_scale_f32 v31, vcc, 1.0, v32, 1.0
	v_mul_f32_e32 v245, v31, v247
	v_fma_f32 v246, -v244, v245, v31
	v_fmac_f32_e32 v245, v246, v247
	v_fma_f32 v31, -v244, v245, v31
	v_div_scale_f32 v244, s[8:9], v33, v33, 1.0
	v_rcp_f32_e32 v246, v244
	v_div_fmas_f32 v31, v31, v247, v245
	v_div_fixup_f32 v31, v31, v32, 1.0
	s_lshl_b32 s8, s52, 12
	v_fma_f32 v32, -v244, v246, 1.0
	v_fmac_f32_e32 v246, v32, v246
	v_div_scale_f32 v32, vcc, 1.0, v33, 1.0
	v_mul_f32_e32 v245, v32, v246
	v_fma_f32 v247, -v244, v245, v32
	v_fmac_f32_e32 v245, v247, v246
	v_fma_f32 v32, -v244, v245, v32
	v_div_fmas_f32 v32, v32, v246, v245
	v_div_fixup_f32 v32, v32, v33, 1.0
	s_add_i32 s8, s8, 0
	v_lshlrev_b32_e32 v33, 1, v135
	v_lshlrev_b32_e32 v244, 9, v136
	v_add3_u32 v33, s8, v33, v244
	v_bfe_u32 v244, v34, 16, 1
	v_add3_u32 v34, v34, v244, s51
	ds_write_b16_d16_hi v33, v34 offset:37888
	v_mul_f32_e32 v34, v50, v241
	v_bfe_u32 v50, v34, 16, 1
	v_add3_u32 v34, v34, v50, s51
	ds_write_b16_d16_hi v33, v34 offset:37952
	v_mul_f32_e32 v34, v35, v240
	v_bfe_u32 v35, v34, 16, 1
	v_add3_u32 v34, v34, v35, s51
	ds_write_b16_d16_hi v33, v34 offset:38016
	v_mul_f32_e32 v34, v51, v240
	v_bfe_u32 v35, v34, 16, 1
	v_add3_u32 v34, v34, v35, s51
	ds_write_b16_d16_hi v33, v34 offset:38080
	v_mul_f32_e32 v34, v36, v242
	v_bfe_u32 v35, v34, 16, 1
	v_add3_u32 v34, v34, v35, s51
	ds_write_b16_d16_hi v33, v34 offset:38144
	v_mul_f32_e32 v34, v52, v242
	v_bfe_u32 v35, v34, 16, 1
	v_add3_u32 v34, v34, v35, s51
	ds_write_b16_d16_hi v33, v34 offset:38208
	v_mul_f32_e32 v34, v37, v243
	v_bfe_u32 v35, v34, 16, 1
	v_add3_u32 v34, v34, v35, s51
	ds_write_b16_d16_hi v33, v34 offset:38272
	v_mul_f32_e32 v34, v53, v243
	v_bfe_u32 v35, v34, 16, 1
	v_add3_u32 v34, v34, v35, s51
	ds_write_b16_d16_hi v33, v34 offset:38336
	v_mul_f32_e32 v34, v38, v26
	v_bfe_u32 v35, v34, 16, 1
	v_add3_u32 v34, v34, v35, s51
	v_mul_f32_e32 v26, v54, v26
	ds_write_b16_d16_hi v33, v34 offset:38912
	v_bfe_u32 v34, v26, 16, 1
	v_add3_u32 v26, v26, v34, s51
	ds_write_b16_d16_hi v33, v26 offset:38976
	v_mul_f32_e32 v26, v39, v27
	v_bfe_u32 v34, v26, 16, 1
	v_add3_u32 v26, v26, v34, s51
	ds_write_b16_d16_hi v33, v26 offset:39040
	v_mul_f32_e32 v26, v55, v27
	v_bfe_u32 v27, v26, 16, 1
	v_add3_u32 v26, v26, v27, s51
	ds_write_b16_d16_hi v33, v26 offset:39104
	v_mul_f32_e32 v26, v40, v28
	v_bfe_u32 v27, v26, 16, 1
	v_add3_u32 v26, v26, v27, s51
	ds_write_b16_d16_hi v33, v26 offset:39168
	v_mul_f32_e32 v26, v56, v28
	v_bfe_u32 v27, v26, 16, 1
	v_add3_u32 v26, v26, v27, s51
	ds_write_b16_d16_hi v33, v26 offset:39232
	v_mul_f32_e32 v26, v41, v29
	v_bfe_u32 v27, v26, 16, 1
	v_add3_u32 v26, v26, v27, s51
	ds_write_b16_d16_hi v33, v26 offset:39296
	v_mul_f32_e32 v26, v57, v29
	v_bfe_u32 v27, v26, 16, 1
	v_add3_u32 v26, v26, v27, s51
	ds_write_b16_d16_hi v33, v26 offset:39360
	v_mul_f32_e32 v26, v42, v21
	v_bfe_u32 v27, v26, 16, 1
	v_add3_u32 v26, v26, v27, s51
	v_mul_f32_e32 v21, v58, v21
	ds_write_b16_d16_hi v33, v26 offset:39936
	v_bfe_u32 v26, v21, 16, 1
	v_add3_u32 v21, v21, v26, s51
	ds_write_b16_d16_hi v33, v21 offset:40000
	v_mul_f32_e32 v21, v43, v22
	v_bfe_u32 v26, v21, 16, 1
	v_add3_u32 v21, v21, v26, s51
	ds_write_b16_d16_hi v33, v21 offset:40064
	v_mul_f32_e32 v21, v59, v22
	v_bfe_u32 v22, v21, 16, 1
	v_add3_u32 v21, v21, v22, s51
	ds_write_b16_d16_hi v33, v21 offset:40128
	v_mul_f32_e32 v21, v44, v23
	v_bfe_u32 v22, v21, 16, 1
	v_add3_u32 v21, v21, v22, s51
	ds_write_b16_d16_hi v33, v21 offset:40192
	v_mul_f32_e32 v21, v60, v23
	v_bfe_u32 v22, v21, 16, 1
	v_add3_u32 v21, v21, v22, s51
	ds_write_b16_d16_hi v33, v21 offset:40256
	v_mul_f32_e32 v21, v45, v24
	v_bfe_u32 v22, v21, 16, 1
	v_add3_u32 v21, v21, v22, s51
	ds_write_b16_d16_hi v33, v21 offset:40320
	v_mul_f32_e32 v21, v61, v24
	v_bfe_u32 v22, v21, 16, 1
	v_add3_u32 v21, v21, v22, s51
	ds_write_b16_d16_hi v33, v21 offset:40384
	v_mul_f32_e32 v21, v46, v25
	v_bfe_u32 v22, v21, 16, 1
	v_add3_u32 v21, v21, v22, s51
	ds_write_b16_d16_hi v33, v21 offset:40960
	v_mul_f32_e32 v21, v62, v25
	v_bfe_u32 v22, v21, 16, 1
	v_add3_u32 v21, v21, v22, s51
	ds_write_b16_d16_hi v33, v21 offset:41024
	v_mul_f32_e32 v21, v47, v30
	v_bfe_u32 v22, v21, 16, 1
	v_add3_u32 v21, v21, v22, s51
	ds_write_b16_d16_hi v33, v21 offset:41088
	v_mul_f32_e32 v21, v63, v30
	v_bfe_u32 v22, v21, 16, 1
	v_add3_u32 v21, v21, v22, s51
	ds_write_b16_d16_hi v33, v21 offset:41152
	v_mul_f32_e32 v21, v48, v31
	v_bfe_u32 v22, v21, 16, 1
	v_add3_u32 v21, v21, v22, s51
	ds_write_b16_d16_hi v33, v21 offset:41216
	v_mul_f32_e32 v21, v64, v31
	v_bfe_u32 v22, v21, 16, 1
	v_add3_u32 v21, v21, v22, s51
	ds_write_b16_d16_hi v33, v21 offset:41280
	v_mul_f32_e32 v21, v49, v32
	v_bfe_u32 v22, v21, 16, 1
	v_add3_u32 v21, v21, v22, s51
	ds_write_b16_d16_hi v33, v21 offset:41344
	v_mul_f32_e32 v21, v65, v32
	v_bfe_u32 v22, v21, 16, 1
	v_add3_u32 v21, v21, v22, s51
	ds_write_b16_d16_hi v33, v21 offset:41408
	v_add_u32_e32 v21, s8, v0
	s_waitcnt lgkmcnt(0)
; #define LAS __attribute__((address_space(3)))
; __device__ __forceinline__ unsigned pk2(float lo, float hi) { typedef __bf16 bf16x2_t_ __attribute__((ext_vector_type(2))); f32x2 v = {lo, hi}; return __builtin_bit_cast(unsigned, __builtin_convertvector(v, bf16x2_t_)); }
; __device__ __forceinline__ void attn_unit(const UnitDesc& u, LAS unsigned char* shm, float qkmax, float thresh) {
;     ...
; #pragma unroll
;         for (int i = 0; i < 4; ++i) { const int row = i * 8 + (lane >> 3), ch = lane & 7;
;             const u32x4 ov = *(const LAS u32x4*)(stg + row * 64 + ch * 8);
;             const u32x4 zv = zv4[i];
;             u32x4 w; w.x = pk2(bflo(ov.x) * bflo(zv.x), bfhi(ov.x) * bfhi(zv.x)); w.y = pk2(bflo(ov.y) * bflo(zv.y), bfhi(ov.y) * bfhi(zv.y));
;             w.z = pk2(bflo(ov.z) * bflo(zv.z), bfhi(ov.z) * bfhi(zv.z)); w.w = pk2(bflo(ov.w) * bflo(zv.w), bfhi(ov.w) * bfhi(zv.w));
;             *(u32x4*)(u.O + (size_t)(wid * 32 + row) * 1024 + ch * 8) = w; }
	v_lshl_add_u32 v22, v20, 7, v21
	ds_read_b128 v[22:25], v22 offset:37888
	v_or_b32_e32 v34, 8, v20
	v_lshl_add_u32 v26, v34, 7, v21
	ds_read_b128 v[26:29], v26 offset:37888
	s_waitcnt vmcnt(3)
	v_lshlrev_b32_e32 v32, 16, v14
	s_waitcnt lgkmcnt(1)
	v_lshlrev_b32_e32 v30, 16, v22
	v_and_b32_e32 v31, 0xffff0000, v22
	v_and_b32_e32 v33, 0xffff0000, v14
	v_pk_mul_f32 v[30:31], v[32:33], v[30:31]
	v_lshlrev_b32_e32 v22, 16, v23
	v_cvt_pk_bf16_f32 v14, v30, v31
	v_and_b32_e32 v23, 0xffff0000, v23
	v_lshlrev_b32_e32 v30, 16, v15
	v_and_b32_e32 v31, 0xffff0000, v15
	v_pk_mul_f32 v[22:23], v[30:31], v[22:23]
	v_lshlrev_b32_e32 v30, 16, v16
	v_cvt_pk_bf16_f32 v15, v22, v23
	v_lshlrev_b32_e32 v22, 16, v24
	v_and_b32_e32 v23, 0xffff0000, v24
	v_and_b32_e32 v31, 0xffff0000, v16
	v_pk_mul_f32 v[22:23], v[30:31], v[22:23]
	v_lshlrev_b32_e32 v24, 16, v17
	v_cvt_pk_bf16_f32 v16, v22, v23
	v_lshlrev_b32_e32 v22, 16, v25
	v_and_b32_e32 v23, 0xffff0000, v25
	v_and_b32_e32 v25, 0xffff0000, v17
	v_pk_mul_f32 v[22:23], v[24:25], v[22:23]
	s_nop 0
	v_cvt_pk_bf16_f32 v17, v22, v23
	global_store_dwordx4 v[18:19], v[14:17], off
	v_or_b32_e32 v22, 16, v20
	v_or_b32_e32 v23, 24, v20
	s_waitcnt lgkmcnt(0)
	v_lshlrev_b32_e32 v14, 16, v26
	v_and_b32_e32 v15, 0xffff0000, v26
	s_waitcnt vmcnt(3)
	v_lshlrev_b32_e32 v16, 16, v10
	v_and_b32_e32 v17, 0xffff0000, v10
	v_pk_mul_f32 v[14:15], v[16:17], v[14:15]
	v_lshlrev_b32_e32 v16, 16, v11
	v_cvt_pk_bf16_f32 v10, v14, v15
	v_lshlrev_b32_e32 v14, 16, v27
	v_and_b32_e32 v15, 0xffff0000, v27
	v_and_b32_e32 v17, 0xffff0000, v11
	v_pk_mul_f32 v[14:15], v[16:17], v[14:15]
	v_lshlrev_b32_e32 v16, 16, v12
	v_cvt_pk_bf16_f32 v11, v14, v15
	v_lshlrev_b32_e32 v14, 16, v28
	v_and_b32_e32 v15, 0xffff0000, v28
	v_and_b32_e32 v17, 0xffff0000, v12
	v_pk_mul_f32 v[14:15], v[16:17], v[14:15]
	v_lshlrev_b32_e32 v16, 16, v13
	v_cvt_pk_bf16_f32 v12, v14, v15
	v_lshlrev_b32_e32 v14, 16, v29
	v_and_b32_e32 v15, 0xffff0000, v29
	v_and_b32_e32 v17, 0xffff0000, v13
	v_pk_mul_f32 v[14:15], v[16:17], v[14:15]
	s_waitcnt vmcnt(2)
	v_lshlrev_b32_e32 v20, 16, v6
	v_cvt_pk_bf16_f32 v13, v14, v15
	v_or_b32_e32 v14, s49, v34
	v_ashrrev_i32_e32 v15, 31, v14
	v_lshlrev_b64 v[14:15], 11, v[14:15]
	v_lshl_add_u64 v[14:15], s[6:7], 0, v[14:15]
	v_lshl_add_u64 v[18:19], v[14:15], 0, v[0:1]
	v_lshl_add_u32 v14, v22, 7, v21
	ds_read_b128 v[14:17], v14 offset:37888
	global_store_dwordx4 v[18:19], v[10:13], off
	s_nop 1
	v_lshl_add_u32 v10, v23, 7, v21
	ds_read_b128 v[10:13], v10 offset:37888
	s_waitcnt lgkmcnt(1)
	v_lshlrev_b32_e32 v18, 16, v14
	v_and_b32_e32 v19, 0xffff0000, v14
	v_and_b32_e32 v21, 0xffff0000, v6
	v_pk_mul_f32 v[18:19], v[20:21], v[18:19]
	v_lshlrev_b32_e32 v14, 16, v15
	v_cvt_pk_bf16_f32 v6, v18, v19
	v_and_b32_e32 v15, 0xffff0000, v15
	v_lshlrev_b32_e32 v18, 16, v7
	v_and_b32_e32 v19, 0xffff0000, v7
	v_pk_mul_f32 v[14:15], v[18:19], v[14:15]
	v_lshlrev_b32_e32 v18, 16, v8
	v_cvt_pk_bf16_f32 v7, v14, v15
	v_lshlrev_b32_e32 v14, 16, v16
	v_and_b32_e32 v15, 0xffff0000, v16
	v_and_b32_e32 v19, 0xffff0000, v8
	v_pk_mul_f32 v[14:15], v[18:19], v[14:15]
	v_lshlrev_b32_e32 v16, 16, v9
	v_cvt_pk_bf16_f32 v8, v14, v15
	v_lshlrev_b32_e32 v14, 16, v17
	v_and_b32_e32 v15, 0xffff0000, v17
	v_and_b32_e32 v17, 0xffff0000, v9
	v_pk_mul_f32 v[14:15], v[16:17], v[14:15]
	s_nop 0
	v_cvt_pk_bf16_f32 v9, v14, v15
	v_or_b32_e32 v14, s49, v22
	v_ashrrev_i32_e32 v15, 31, v14
	v_lshlrev_b64 v[14:15], 11, v[14:15]
	v_lshl_add_u64 v[14:15], s[6:7], 0, v[14:15]
	v_lshl_add_u64 v[14:15], v[14:15], 0, v[0:1]
	global_store_dwordx4 v[14:15], v[6:9], off
	s_waitcnt lgkmcnt(0)
	s_nop 0
	v_lshlrev_b32_e32 v6, 16, v10
	v_and_b32_e32 v7, 0xffff0000, v10
	s_waitcnt vmcnt(3)
	v_lshlrev_b32_e32 v8, 16, v2
	v_and_b32_e32 v9, 0xffff0000, v2
	v_pk_mul_f32 v[6:7], v[8:9], v[6:7]
	v_lshlrev_b32_e32 v8, 16, v3
	v_cvt_pk_bf16_f32 v2, v6, v7
	v_lshlrev_b32_e32 v6, 16, v11
	v_and_b32_e32 v7, 0xffff0000, v11
	v_and_b32_e32 v9, 0xffff0000, v3
	v_pk_mul_f32 v[6:7], v[8:9], v[6:7]
	v_lshlrev_b32_e32 v8, 16, v4
	v_cvt_pk_bf16_f32 v3, v6, v7
	v_lshlrev_b32_e32 v6, 16, v12
	v_and_b32_e32 v7, 0xffff0000, v12
	v_and_b32_e32 v9, 0xffff0000, v4
	v_pk_mul_f32 v[6:7], v[8:9], v[6:7]
	v_lshlrev_b32_e32 v8, 16, v5
	v_cvt_pk_bf16_f32 v4, v6, v7
	v_lshlrev_b32_e32 v6, 16, v13
	v_and_b32_e32 v7, 0xffff0000, v13
	v_and_b32_e32 v9, 0xffff0000, v5
	v_pk_mul_f32 v[6:7], v[8:9], v[6:7]
	s_nop 0
	v_cvt_pk_bf16_f32 v5, v6, v7
	v_or_b32_e32 v6, s49, v23
	v_ashrrev_i32_e32 v7, 31, v6
	v_lshlrev_b64 v[6:7], 11, v[6:7]
	v_lshl_add_u64 v[6:7], s[6:7], 0, v[6:7]
	v_lshl_add_u64 v[6:7], v[6:7], 0, v[0:1]
	global_store_dwordx4 v[6:7], v[2:5], off

; #define LAS __attribute__((address_space(3)))
; __device__ __forceinline__ void attn_unit(const UnitDesc& u, LAS unsigned char* shm, float qkmax, float thresh) {
;     ...
;     asm volatile("s_waitcnt vmcnt(0)" : "+v"(kA), "+v"(vA), "+v"(kB), "+v"(vB), "+v"(kC), "+v"(vC), "+v"(lA), "+v"(lB), "+v"(lC) :: "memory");
;     if (active) {
;         u32x4 zv4[4];
; #pragma unroll
;         for (int i = 0; i < 4; ++i) zv4[i] = *(const u32x4*)(u.Zg + (size_t)(wid * 32 + i * 8 + (lane >> 3)) * 512 + (lane & 7) * 8);
;         { auto rr = __builtin_amdgcn_permlane32_swap(__float_as_uint(l_reg), __float_as_uint(l_reg), false, false); l_reg = __uint_as_float(rr[0]) + __uint_as_float(rr[1]); }
;         LAS float* lx = (LAS float*)(shm + LDS_LX) + wid * 32;
;         if (hi == 0) lx[r32] = l_reg;
;         asm volatile("s_waitcnt lgkmcnt(0)" ::: "memory");
.LBB0_829:
	s_or_b64 exec, exec, s[62:63]
	s_nop 0
	s_and_b64 vcc, exec, s[12:13]
	s_cbranch_vccnz .LBB0_719
	s_nop 7
	s_nop 7
	v_mov_b64_e32 v[34:35], v[2:3]
	v_mov_b64_e32 v[36:37], v[4:5]
	v_mov_b64_e32 v[38:39], v[6:7]
	v_mov_b64_e32 v[40:41], v[8:9]
	v_mov_b64_e32 v[42:43], v[10:11]
	v_mov_b64_e32 v[44:45], v[12:13]
	v_mov_b64_e32 v[46:47], v[14:15]
	v_mov_b64_e32 v[48:49], v[16:17]
	v_mov_b64_e32 v[50:51], v[18:19]
	v_mov_b64_e32 v[52:53], v[20:21]
	v_mov_b64_e32 v[54:55], v[22:23]
	v_mov_b64_e32 v[56:57], v[24:25]
	v_mov_b64_e32 v[58:59], v[26:27]
	v_mov_b64_e32 v[60:61], v[28:29]
	v_mov_b64_e32 v[62:63], v[30:31]
	v_mov_b64_e32 v[64:65], v[32:33]
	s_lshl_b64 s[6:7], s[44:45], 1
	s_add_u32 s8, s24, s6
	v_lshrrev_b32_e32 v20, 3, v137
	s_addc_u32 s9, s25, s7
	s_lshl_b64 s[6:7], s[46:47], 1
	v_or_b32_e32 v18, s49, v20
	s_add_u32 s8, s8, s6
	v_and_b32_e32 v0, 56, v138
	v_or_b32_e32 v6, 8, v18
	s_addc_u32 s9, s9, s7
	v_lshlrev_b32_e32 v0, 1, v0
	v_ashrrev_i32_e32 v19, 31, v18
	v_ashrrev_i32_e32 v7, 31, v6
	v_lshl_add_u64 v[2:3], s[8:9], 0, v[0:1]
	v_lshlrev_b64 v[4:5], 10, v[18:19]
	v_lshlrev_b64 v[6:7], 10, v[6:7]
	v_lshl_add_u64 v[4:5], v[2:3], 0, v[4:5]
	v_lshl_add_u64 v[6:7], v[2:3], 0, v[6:7]
	global_load_dwordx4 v[14:17], v[4:5], off
	global_load_dwordx4 v[10:13], v[6:7], off
	v_or_b32_e32 v4, 16, v18
	v_or_b32_e32 v6, 24, v18
	v_ashrrev_i32_e32 v5, 31, v4
	v_ashrrev_i32_e32 v7, 31, v6
	v_lshlrev_b64 v[4:5], 10, v[4:5]
	v_lshlrev_b64 v[6:7], 10, v[6:7]
	v_lshl_add_u64 v[4:5], v[2:3], 0, v[4:5]
	v_lshl_add_u64 v[2:3], v[2:3], 0, v[6:7]
	global_load_dwordx4 v[6:9], v[4:5], off
	s_nop 0
	global_load_dwordx4 v[2:5], v[2:3], off
	v_mov_b32_e32 v21, v148
	s_lshl_b32 s8, s49, 2
	s_nop 0
	v_permlane32_swap_b32_e32 v148, v21
	s_add_i32 s10, s8, 0
	v_cmp_gt_u32_e32 vcc, 32, v137
	s_and_saveexec_b64 s[8:9], vcc
	s_cbranch_execz .LBB0_718
	v_add_f32_e32 v21, v148, v21
	v_lshl_add_u32 v22, v135, 2, s10
	ds_write_b32 v22, v21 offset:36864
	s_branch .LBB0_718
